# v64 + DSA top-k bit-search loops rewritten: compares into separate SGPR pairs, carry-in accumulate, no per-element s_nop
# baseline (speedup 1.0000x reference)
.LBB0_763:
	s_lshl_b32 s5, 1, s4
	v_or_b32_e32 v1, s5, v0
	s_add_i32 s4, s4, -1
	v_mov_b32_e32 v2, 0
	v_mov_b32_e32 v3, 0
	v_cmp_ge_u32_e64 s[70:71], v32, v1
	v_cmp_ge_u32_e64 s[72:73], v33, v1
	v_cmp_ge_u32_e64 s[74:75], v34, v1
	v_cmp_ge_u32_e64 s[76:77], v35, v1
	v_cmp_ge_u32_e64 s[78:79], v36, v1
	v_cmp_ge_u32_e64 s[80:81], v37, v1
	v_cmp_ge_u32_e64 s[82:83], v38, v1
	v_cmp_ge_u32_e64 s[84:85], v39, v1
	v_addc_co_u32_e64 v2, s[86:87], 0, v2, s[70:71]
	v_addc_co_u32_e64 v3, s[86:87], 0, v3, s[72:73]
	v_addc_co_u32_e64 v2, s[86:87], 0, v2, s[74:75]
	v_addc_co_u32_e64 v3, s[86:87], 0, v3, s[76:77]
	v_cmp_ge_u32_e64 s[70:71], v40, v1
	v_cmp_ge_u32_e64 s[72:73], v41, v1
	v_cmp_ge_u32_e64 s[74:75], v42, v1
	v_cmp_ge_u32_e64 s[76:77], v43, v1
	v_addc_co_u32_e64 v2, s[86:87], 0, v2, s[78:79]
	v_addc_co_u32_e64 v3, s[86:87], 0, v3, s[80:81]
	v_addc_co_u32_e64 v2, s[86:87], 0, v2, s[82:83]
	v_addc_co_u32_e64 v3, s[86:87], 0, v3, s[84:85]
	v_cmp_ge_u32_e64 s[78:79], v44, v1
	v_cmp_ge_u32_e64 s[80:81], v45, v1
	v_cmp_ge_u32_e64 s[82:83], v46, v1
	v_cmp_ge_u32_e64 s[84:85], v47, v1
	v_addc_co_u32_e64 v2, s[86:87], 0, v2, s[70:71]
	v_addc_co_u32_e64 v3, s[86:87], 0, v3, s[72:73]
	v_addc_co_u32_e64 v2, s[86:87], 0, v2, s[74:75]
	v_addc_co_u32_e64 v3, s[86:87], 0, v3, s[76:77]
	v_cmp_ge_u32_e64 s[70:71], v48, v1
	v_cmp_ge_u32_e64 s[72:73], v49, v1
	v_cmp_ge_u32_e64 s[74:75], v50, v1
	v_cmp_ge_u32_e64 s[76:77], v51, v1
	v_addc_co_u32_e64 v2, s[86:87], 0, v2, s[78:79]
	v_addc_co_u32_e64 v3, s[86:87], 0, v3, s[80:81]
	v_addc_co_u32_e64 v2, s[86:87], 0, v2, s[82:83]
	v_addc_co_u32_e64 v3, s[86:87], 0, v3, s[84:85]
	v_cmp_ge_u32_e64 s[78:79], v52, v1
	v_cmp_ge_u32_e64 s[80:81], v53, v1
	v_cmp_ge_u32_e64 s[82:83], v54, v1
	v_cmp_ge_u32_e64 s[84:85], v55, v1
	v_addc_co_u32_e64 v2, s[86:87], 0, v2, s[70:71]
	v_addc_co_u32_e64 v3, s[86:87], 0, v3, s[72:73]
	v_addc_co_u32_e64 v2, s[86:87], 0, v2, s[74:75]
	v_addc_co_u32_e64 v3, s[86:87], 0, v3, s[76:77]
	v_cmp_ge_u32_e64 s[70:71], v56, v1
	v_cmp_ge_u32_e64 s[72:73], v57, v1
	v_cmp_ge_u32_e64 s[74:75], v58, v1
	v_cmp_ge_u32_e64 s[76:77], v59, v1
	v_addc_co_u32_e64 v2, s[86:87], 0, v2, s[78:79]
	v_addc_co_u32_e64 v3, s[86:87], 0, v3, s[80:81]
	v_addc_co_u32_e64 v2, s[86:87], 0, v2, s[82:83]
	v_addc_co_u32_e64 v3, s[86:87], 0, v3, s[84:85]
	v_cmp_ge_u32_e64 s[78:79], v60, v1
	v_cmp_ge_u32_e64 s[80:81], v61, v1
	v_cmp_ge_u32_e64 s[82:83], v62, v1
	v_cmp_ge_u32_e64 s[84:85], v63, v1
	v_addc_co_u32_e64 v2, s[86:87], 0, v2, s[70:71]
	v_addc_co_u32_e64 v3, s[86:87], 0, v3, s[72:73]
	v_addc_co_u32_e64 v2, s[86:87], 0, v2, s[74:75]
	v_addc_co_u32_e64 v3, s[86:87], 0, v3, s[76:77]
	v_addc_co_u32_e64 v2, s[86:87], 0, v2, s[78:79]
	v_addc_co_u32_e64 v3, s[86:87], 0, v3, s[80:81]
	v_addc_co_u32_e64 v2, s[86:87], 0, v2, s[82:83]
	v_addc_co_u32_e64 v3, s[86:87], 0, v3, s[84:85]
	v_add_u32_e32 v2, v2, v3
	v_cvt_f32_u32_e32 v2, v2
	s_nop 1
	v_add_f32_dpp v2, v2, v2 quad_perm:[1,0,3,2] row_mask:0xf bank_mask:0xf bound_ctrl:1
	s_nop 1
	v_add_f32_dpp v2, v2, v2 quad_perm:[2,3,0,1] row_mask:0xf bank_mask:0xf bound_ctrl:1
	s_nop 1
	v_add_f32_dpp v2, v2, v2 row_half_mirror row_mask:0xf bank_mask:0xf bound_ctrl:1
	s_nop 1
	v_add_f32_dpp v2, v2, v2 row_mirror row_mask:0xf bank_mask:0xf bound_ctrl:1
	s_nop 0
	v_readlane_b32 s5, v2, 16
	v_readlane_b32 s65, v2, 48
	v_readlane_b32 s6, v2, 0
	v_readlane_b32 s7, v2, 32
	v_mov_b32_e32 v2, s5
	v_mov_b32_e32 v3, s65
	v_pk_add_f32 v[2:3], s[6:7], v[2:3]
	s_nop 0
	v_add_f32_e32 v2, v2, v3
	v_cvt_i32_f32_e32 v2, v2
	v_cmp_lt_i32_e32 vcc, s66, v2
	s_nop 1
	v_cndmask_b32_e32 v0, v0, v1, vcc
	s_cmp_lg_u32 s4, -1
	s_cbranch_scc1 .LBB0_763
	s_branch .LBB0_770

.LBB0_769:
	s_lshl_b32 s5, 1, s4
	v_or_b32_e32 v1, s5, v0
	s_add_i32 s4, s4, -1
	v_mov_b32_e32 v2, 0
	v_mov_b32_e32 v3, 0
	v_cmp_ge_u32_e64 s[70:71], v32, v1
	v_cmp_ge_u32_e64 s[72:73], v33, v1
	v_cmp_ge_u32_e64 s[74:75], v34, v1
	v_cmp_ge_u32_e64 s[76:77], v35, v1
	v_cmp_ge_u32_e64 s[78:79], v36, v1
	v_cmp_ge_u32_e64 s[80:81], v37, v1
	v_cmp_ge_u32_e64 s[82:83], v38, v1
	v_cmp_ge_u32_e64 s[84:85], v39, v1
	v_addc_co_u32_e64 v2, s[86:87], 0, v2, s[70:71]
	v_addc_co_u32_e64 v3, s[86:87], 0, v3, s[72:73]
	v_addc_co_u32_e64 v2, s[86:87], 0, v2, s[74:75]
	v_addc_co_u32_e64 v3, s[86:87], 0, v3, s[76:77]
	v_cmp_ge_u32_e64 s[70:71], v40, v1
	v_cmp_ge_u32_e64 s[72:73], v41, v1
	v_cmp_ge_u32_e64 s[74:75], v42, v1
	v_cmp_ge_u32_e64 s[76:77], v43, v1
	v_addc_co_u32_e64 v2, s[86:87], 0, v2, s[78:79]
	v_addc_co_u32_e64 v3, s[86:87], 0, v3, s[80:81]
	v_addc_co_u32_e64 v2, s[86:87], 0, v2, s[82:83]
	v_addc_co_u32_e64 v3, s[86:87], 0, v3, s[84:85]
	v_cmp_ge_u32_e64 s[78:79], v44, v1
	v_cmp_ge_u32_e64 s[80:81], v45, v1
	v_cmp_ge_u32_e64 s[82:83], v46, v1
	v_cmp_ge_u32_e64 s[84:85], v47, v1
	v_addc_co_u32_e64 v2, s[86:87], 0, v2, s[70:71]
	v_addc_co_u32_e64 v3, s[86:87], 0, v3, s[72:73]
	v_addc_co_u32_e64 v2, s[86:87], 0, v2, s[74:75]
	v_addc_co_u32_e64 v3, s[86:87], 0, v3, s[76:77]
	v_cmp_ge_u32_e64 s[70:71], v48, v1
	v_cmp_ge_u32_e64 s[72:73], v49, v1
	v_cmp_ge_u32_e64 s[74:75], v50, v1
	v_cmp_ge_u32_e64 s[76:77], v51, v1
	v_addc_co_u32_e64 v2, s[86:87], 0, v2, s[78:79]
	v_addc_co_u32_e64 v3, s[86:87], 0, v3, s[80:81]
	v_addc_co_u32_e64 v2, s[86:87], 0, v2, s[82:83]
	v_addc_co_u32_e64 v3, s[86:87], 0, v3, s[84:85]
	v_cmp_ge_u32_e64 s[78:79], v52, v1
	v_cmp_ge_u32_e64 s[80:81], v53, v1
	v_cmp_ge_u32_e64 s[82:83], v54, v1
	v_cmp_ge_u32_e64 s[84:85], v55, v1
	v_addc_co_u32_e64 v2, s[86:87], 0, v2, s[70:71]
	v_addc_co_u32_e64 v3, s[86:87], 0, v3, s[72:73]
	v_addc_co_u32_e64 v2, s[86:87], 0, v2, s[74:75]
	v_addc_co_u32_e64 v3, s[86:87], 0, v3, s[76:77]
	v_addc_co_u32_e64 v2, s[86:87], 0, v2, s[78:79]
	v_addc_co_u32_e64 v3, s[86:87], 0, v3, s[80:81]
	v_addc_co_u32_e64 v2, s[86:87], 0, v2, s[82:83]
	v_addc_co_u32_e64 v3, s[86:87], 0, v3, s[84:85]
	v_add_u32_e32 v2, v2, v3
	v_cvt_f32_u32_e32 v2, v2
	s_nop 1
	v_add_f32_dpp v2, v2, v2 quad_perm:[1,0,3,2] row_mask:0xf bank_mask:0xf bound_ctrl:1
	s_nop 1
	v_add_f32_dpp v2, v2, v2 quad_perm:[2,3,0,1] row_mask:0xf bank_mask:0xf bound_ctrl:1
	s_nop 1
	v_add_f32_dpp v2, v2, v2 row_half_mirror row_mask:0xf bank_mask:0xf bound_ctrl:1
	s_nop 1
	v_add_f32_dpp v2, v2, v2 row_mirror row_mask:0xf bank_mask:0xf bound_ctrl:1
	s_nop 0
	v_readlane_b32 s5, v2, 16
	v_readlane_b32 s65, v2, 48
	v_readlane_b32 s6, v2, 0
	v_readlane_b32 s7, v2, 32
	v_mov_b32_e32 v2, s5
	v_mov_b32_e32 v3, s65
	v_pk_add_f32 v[2:3], s[6:7], v[2:3]
	s_nop 0
	v_add_f32_e32 v2, v2, v3
	v_cvt_i32_f32_e32 v2, v2
	v_cmp_lt_i32_e32 vcc, s66, v2
	s_nop 1
	v_cndmask_b32_e32 v0, v0, v1, vcc
	s_cmp_eq_u32 s4, -1
	s_cbranch_scc0 .LBB0_769

.LBB0_772:
	s_lshl_b32 s5, 1, s4
	v_or_b32_e32 v1, s5, v0
	s_add_i32 s4, s4, -1
	v_mov_b32_e32 v2, 0
	v_mov_b32_e32 v3, 0
	v_cmp_ge_u32_e64 s[70:71], v32, v1
	v_cmp_ge_u32_e64 s[72:73], v33, v1
	v_cmp_ge_u32_e64 s[74:75], v34, v1
	v_cmp_ge_u32_e64 s[76:77], v35, v1
	v_cmp_ge_u32_e64 s[78:79], v36, v1
	v_cmp_ge_u32_e64 s[80:81], v37, v1
	v_cmp_ge_u32_e64 s[82:83], v38, v1
	v_cmp_ge_u32_e64 s[84:85], v39, v1
	v_addc_co_u32_e64 v2, s[86:87], 0, v2, s[70:71]
	v_addc_co_u32_e64 v3, s[86:87], 0, v3, s[72:73]
	v_addc_co_u32_e64 v2, s[86:87], 0, v2, s[74:75]
	v_addc_co_u32_e64 v3, s[86:87], 0, v3, s[76:77]
	v_cmp_ge_u32_e64 s[70:71], v40, v1
	v_cmp_ge_u32_e64 s[72:73], v41, v1
	v_cmp_ge_u32_e64 s[74:75], v42, v1
	v_cmp_ge_u32_e64 s[76:77], v43, v1
	v_addc_co_u32_e64 v2, s[86:87], 0, v2, s[78:79]
	v_addc_co_u32_e64 v3, s[86:87], 0, v3, s[80:81]
	v_addc_co_u32_e64 v2, s[86:87], 0, v2, s[82:83]
	v_addc_co_u32_e64 v3, s[86:87], 0, v3, s[84:85]
	v_cmp_ge_u32_e64 s[78:79], v44, v1
	v_cmp_ge_u32_e64 s[80:81], v45, v1
	v_cmp_ge_u32_e64 s[82:83], v46, v1
	v_cmp_ge_u32_e64 s[84:85], v47, v1
	v_addc_co_u32_e64 v2, s[86:87], 0, v2, s[70:71]
	v_addc_co_u32_e64 v3, s[86:87], 0, v3, s[72:73]
	v_addc_co_u32_e64 v2, s[86:87], 0, v2, s[74:75]
	v_addc_co_u32_e64 v3, s[86:87], 0, v3, s[76:77]
	v_addc_co_u32_e64 v2, s[86:87], 0, v2, s[78:79]
	v_addc_co_u32_e64 v3, s[86:87], 0, v3, s[80:81]
	v_addc_co_u32_e64 v2, s[86:87], 0, v2, s[82:83]
	v_addc_co_u32_e64 v3, s[86:87], 0, v3, s[84:85]
	v_add_u32_e32 v2, v2, v3
	v_cvt_f32_u32_e32 v2, v2
	s_nop 1
	v_add_f32_dpp v2, v2, v2 quad_perm:[1,0,3,2] row_mask:0xf bank_mask:0xf bound_ctrl:1
	s_nop 1
	v_add_f32_dpp v2, v2, v2 quad_perm:[2,3,0,1] row_mask:0xf bank_mask:0xf bound_ctrl:1
	s_nop 1
	v_add_f32_dpp v2, v2, v2 row_half_mirror row_mask:0xf bank_mask:0xf bound_ctrl:1
	s_nop 1
	v_add_f32_dpp v2, v2, v2 row_mirror row_mask:0xf bank_mask:0xf bound_ctrl:1
	s_nop 0
	v_readlane_b32 s5, v2, 16
	v_readlane_b32 s65, v2, 48
	v_readlane_b32 s6, v2, 0
	v_readlane_b32 s7, v2, 32
	v_mov_b32_e32 v2, s5
	v_mov_b32_e32 v3, s65
	v_pk_add_f32 v[2:3], s[6:7], v[2:3]
	s_nop 0
	v_add_f32_e32 v2, v2, v3
	v_cvt_i32_f32_e32 v2, v2
	v_cmp_lt_i32_e32 vcc, s66, v2
	s_nop 1
	v_cndmask_b32_e32 v0, v0, v1, vcc
	s_cmp_eq_u32 s4, -1
	s_cbranch_scc0 .LBB0_772

.LBB0_775:
	s_lshl_b32 s5, 1, s4
	v_or_b32_e32 v1, s5, v0
	s_add_i32 s4, s4, -1
	v_mov_b32_e32 v2, 0
	v_mov_b32_e32 v3, 0
	v_cmp_ge_u32_e64 s[70:71], v32, v1
	v_cmp_ge_u32_e64 s[72:73], v33, v1
	v_cmp_ge_u32_e64 s[74:75], v34, v1
	v_cmp_ge_u32_e64 s[76:77], v35, v1
	v_cmp_ge_u32_e64 s[78:79], v36, v1
	v_cmp_ge_u32_e64 s[80:81], v37, v1
	v_cmp_ge_u32_e64 s[82:83], v38, v1
	v_cmp_ge_u32_e64 s[84:85], v39, v1
	v_addc_co_u32_e64 v2, s[86:87], 0, v2, s[70:71]
	v_addc_co_u32_e64 v3, s[86:87], 0, v3, s[72:73]
	v_addc_co_u32_e64 v2, s[86:87], 0, v2, s[74:75]
	v_addc_co_u32_e64 v3, s[86:87], 0, v3, s[76:77]
	v_addc_co_u32_e64 v2, s[86:87], 0, v2, s[78:79]
	v_addc_co_u32_e64 v3, s[86:87], 0, v3, s[80:81]
	v_addc_co_u32_e64 v2, s[86:87], 0, v2, s[82:83]
	v_addc_co_u32_e64 v3, s[86:87], 0, v3, s[84:85]
	v_add_u32_e32 v2, v2, v3
	v_cvt_f32_u32_e32 v2, v2
	s_nop 1
	v_add_f32_dpp v2, v2, v2 quad_perm:[1,0,3,2] row_mask:0xf bank_mask:0xf bound_ctrl:1
	s_nop 1
	v_add_f32_dpp v2, v2, v2 quad_perm:[2,3,0,1] row_mask:0xf bank_mask:0xf bound_ctrl:1
	s_nop 1
	v_add_f32_dpp v2, v2, v2 row_half_mirror row_mask:0xf bank_mask:0xf bound_ctrl:1
	s_nop 1
	v_add_f32_dpp v2, v2, v2 row_mirror row_mask:0xf bank_mask:0xf bound_ctrl:1
	s_nop 0
	v_readlane_b32 s5, v2, 16
	v_readlane_b32 s65, v2, 48
	v_readlane_b32 s6, v2, 0
	v_readlane_b32 s7, v2, 32
	v_mov_b32_e32 v2, s5
	v_mov_b32_e32 v3, s65
	v_pk_add_f32 v[2:3], s[6:7], v[2:3]
	s_nop 0
	v_add_f32_e32 v2, v2, v3
	v_cvt_i32_f32_e32 v2, v2
	v_cmp_lt_i32_e32 vcc, s66, v2
	s_nop 1
	v_cndmask_b32_e32 v0, v0, v1, vcc
	s_cmp_eq_u32 s4, -1
	s_cbranch_scc0 .LBB0_775
